# v13 + persistent softmax-reference broadcast registers in the latent and dilated mixers (freed one constant-holding VGPR to get a 16-wide block)
# speedup vs baseline: 1.0097x; 1.0097x over previous
.LBB0_6:
	s_or_b64 exec, exec, s[4:5]
	s_load_dwordx16 s[36:51], s[0:1], 0x0
	s_load_dwordx16 s[52:67], s[0:1], 0x40
	s_cmp_ge_i32 s26, s27
	s_waitcnt lgkmcnt(0)
	v_writelane_b32 v251, s52, 7
	s_nop 1
	v_writelane_b32 v251, s53, 8
	v_writelane_b32 v251, s54, 9
	v_writelane_b32 v251, s55, 10
	v_writelane_b32 v251, s56, 11
	v_writelane_b32 v251, s57, 12
	v_writelane_b32 v251, s58, 13
	v_writelane_b32 v251, s59, 14
	v_writelane_b32 v251, s60, 15
	v_writelane_b32 v251, s61, 16
	v_writelane_b32 v251, s62, 17
	v_writelane_b32 v251, s63, 18
	v_writelane_b32 v251, s64, 19
	v_writelane_b32 v251, s65, 20
	v_writelane_b32 v251, s66, 21
	v_writelane_b32 v251, s67, 22
	s_load_dwordx16 s[52:67], s[0:1], 0x80
	s_waitcnt lgkmcnt(0)
	v_writelane_b32 v251, s52, 23
	s_nop 1
	v_writelane_b32 v251, s53, 24
	v_writelane_b32 v251, s54, 25
	v_writelane_b32 v251, s55, 26
	v_writelane_b32 v251, s56, 27
	v_writelane_b32 v251, s57, 28
	v_writelane_b32 v251, s58, 29
	v_writelane_b32 v251, s59, 30
	v_writelane_b32 v251, s60, 31
	v_writelane_b32 v251, s61, 32
	v_writelane_b32 v251, s62, 33
	v_writelane_b32 v251, s63, 34
	v_writelane_b32 v251, s64, 35
	v_writelane_b32 v251, s65, 36
	v_writelane_b32 v251, s66, 37
	v_writelane_b32 v251, s67, 38
	s_load_dwordx16 s[52:67], s[0:1], 0xc0
	s_waitcnt lgkmcnt(0)
	v_writelane_b32 v251, s52, 39
	s_nop 1
	v_writelane_b32 v251, s53, 40
	v_writelane_b32 v251, s54, 41
	v_writelane_b32 v251, s55, 42
	v_writelane_b32 v251, s56, 43
	v_writelane_b32 v251, s57, 44
	v_writelane_b32 v251, s58, 45
	v_writelane_b32 v251, s59, 46
	v_writelane_b32 v251, s60, 47
	v_writelane_b32 v251, s61, 48
	v_writelane_b32 v251, s62, 49
	v_writelane_b32 v251, s63, 50
	v_writelane_b32 v251, s64, 51
	v_writelane_b32 v251, s65, 52
	v_writelane_b32 v251, s66, 53
	v_writelane_b32 v251, s67, 54
	s_cbranch_scc1 .LBB0_704
	s_add_u32 s30, s88, 0x10000
	s_addc_u32 s31, s89, 0
	s_add_u32 s34, s88, 0x60000
	s_addc_u32 s35, s89, 0
	s_add_u32 s96, s88, 0x100000
	s_addc_u32 s97, s89, 0
	s_add_u32 s0, s88, 0x9500000
	s_addc_u32 s1, s89, 0
	v_writelane_b32 v251, s0, 55
	v_lshrrev_b32_e32 v1, 20, v0
	v_lshrrev_b32_e32 v0, 10, v0
	v_writelane_b32 v251, s1, 56
	s_add_u32 s0, s88, 0xf500000
	s_addc_u32 s1, s89, 0
	v_writelane_b32 v251, s0, 57
	v_or_b32_e32 v0, v0, v1
	s_mov_b32 s12, s26
	v_writelane_b32 v251, s1, 58
	s_add_u32 s0, s88, 0x1e500000
	s_addc_u32 s1, s89, 0
	v_writelane_b32 v251, s0, 59
	v_mbcnt_lo_u32_b32 v2, -1, 0
	v_mov_b32_e32 v207, 0x358637bd
	v_writelane_b32 v251, s1, 60
	s_add_u32 s0, s88, 0x22100000
	s_addc_u32 s1, s89, 0
	v_writelane_b32 v251, s0, 61
	v_mov_b32_e32 v208, 0x260
	v_mov_b32_e32 v209, 1
	v_writelane_b32 v251, s1, 62
	s_add_u32 s0, s88, 0x24500000
	s_addc_u32 s1, s89, 0
	v_writelane_b32 v251, s0, 63
	v_mbcnt_hi_u32_b32 v210, -1, v2
	v_readlane_b32 s52, v251, 39
	v_writelane_b32 v252, s1, 0
	s_add_u32 s0, s88, 0x26900000
	s_addc_u32 s1, s89, 0
	v_writelane_b32 v252, s0, 1
	v_readlane_b32 s64, v251, 51
	v_readlane_b32 s65, v251, 52
	v_writelane_b32 v252, s1, 2
	s_add_u32 s0, s88, 0x28100000
	s_addc_u32 s1, s89, 0
	v_writelane_b32 v252, s0, 3
	v_readlane_b32 s58, v251, 45
	v_readlane_b32 s59, v251, 46
	v_writelane_b32 v252, s1, 4
	s_add_u32 s0, s88, 0x2e500000
	s_addc_u32 s1, s89, 0
	v_writelane_b32 v252, s0, 5
	v_readlane_b32 s57, v251, 44
	v_readlane_b32 s63, v251, 50
	v_writelane_b32 v252, s1, 6
	s_add_u32 s0, s88, 0x34100000
	s_addc_u32 s1, s89, 0
	v_writelane_b32 v252, s0, 7
	v_readlane_b32 s56, v251, 43
	v_readlane_b32 s66, v251, 53
	v_writelane_b32 v252, s1, 8
	s_add_u32 s0, s88, 0x3e100000
	s_addc_u32 s1, s89, 0
	v_writelane_b32 v252, s0, 9
	v_mov_b32_e32 v212, 0x41b17218
	v_mov_b32_e32 v211, 0xd68
	v_writelane_b32 v252, s1, 10
	s_add_u32 s0, s88, 0x3e400000
	v_writelane_b32 v252, s0, 11
	s_addc_u32 s0, s89, 0
	v_writelane_b32 v252, s0, 12
	v_readlane_b32 s0, v251, 0
	s_lshl_b32 s1, s0, 3
	s_lshl_b32 s4, s98, 3
	s_add_i32 s5, s25, 1
	s_add_u32 s6, s88, 0x4200000
	v_writelane_b32 v252, s5, 13
	s_addc_u32 s7, s89, 0
	v_writelane_b32 v252, s6, 14
	s_mov_b32 s57, s1
	v_mov_b32_e32 v213, 0xf78
	v_writelane_b32 v252, s7, 15
	s_add_u32 s6, s88, 0x1a00000
	s_addc_u32 s7, s89, 0
	v_writelane_b32 v252, s6, 16
	v_mov_b32_e32 v250, 0x1398
	v_writelane_b32 v252, s7, 17
	s_add_u32 s6, s88, 0x3a00000
	s_addc_u32 s7, s89, 0
	v_writelane_b32 v252, s6, 18
	s_movk_i32 s84, 0x2800
	s_mov_b32 s85, 0xc000
	v_writelane_b32 v252, s7, 19
	s_add_u32 s6, s88, 0x9200000
	s_addc_u32 s7, s89, 0
	v_writelane_b32 v252, s6, 20
	s_mov_b32 s86, 0xff61b1e6
	s_mov_b32 s87, 0x41000000
	v_writelane_b32 v252, s7, 21
	s_add_u32 s6, s88, 0x4a00000
	s_addc_u32 s7, s89, 0
	v_writelane_b32 v252, s6, 22
	s_mov_b32 s91, 0xf800000
	s_movk_i32 s56, 0x3000
	v_writelane_b32 v252, s7, 23
	s_add_u32 s6, s88, 0x9440000
	s_addc_u32 s7, s89, 0
	v_writelane_b32 v252, s6, 24
	s_mov_b32 s66, 0x409b43d5
	s_movk_i32 s69, 0x6100
	v_writelane_b32 v252, s7, 25
	s_add_u32 s6, s88, 0xf500c00
	s_addc_u32 s7, s89, 0
	v_writelane_b32 v252, s6, 26
	s_mov_b32 s93, 0
	s_mov_b64 s[20:21], 0x80
	v_writelane_b32 v252, s7, 27
	s_add_u32 s6, s88, 0x93c0000
	s_addc_u32 s7, s89, 0
	v_writelane_b32 v252, s6, 28
	s_mov_b64 s[74:75], 0x100
	v_readlane_b32 s53, v251, 40
	v_writelane_b32 v252, s7, 29
	s_add_u32 s6, s88, 0xf500800
	s_addc_u32 s7, s89, 0
	v_writelane_b32 v252, s6, 30
	v_readlane_b32 s54, v251, 41
	v_readlane_b32 s55, v251, 42
	v_writelane_b32 v252, s7, 31
	s_add_u32 s6, s88, 0x9300000
	s_addc_u32 s7, s89, 0
	v_writelane_b32 v252, s6, 32
	v_readlane_b32 s60, v251, 47
	v_readlane_b32 s61, v251, 48
	v_writelane_b32 v252, s7, 33
	s_add_u32 s6, s88, 0x1500000
	s_addc_u32 s7, s89, 0
	v_writelane_b32 v252, s6, 34
	s_ashr_i32 s90, s98, 31
	s_lshl_b32 s0, s0, 9
	v_writelane_b32 v252, s7, 35
	s_lshl_b32 s13, s98, 9
	v_writelane_b32 v252, s0, 36
	s_add_u32 s0, s88, 0x8a00000
	v_writelane_b32 v252, s0, 37
	s_addc_u32 s0, s89, 0
	v_writelane_b32 v252, s0, 38
	s_add_u32 s0, s88, 0x6a00000
	v_writelane_b32 v252, s0, 39
	s_addc_u32 s0, s89, 0
	s_cmp_lg_u64 s[64:65], 0
	v_writelane_b32 v252, s0, 40
	s_cselect_b64 s[6:7], -1, 0
	v_writelane_b32 v252, s6, 41
	s_cmp_lg_u64 s[58:59], 0
	s_cselect_b64 s[0:1], -1, 0
	v_writelane_b32 v252, s7, 42
	v_writelane_b32 v252, s0, 43
	s_mov_b32 s58, s4
	s_mov_b32 s59, 0x7f800000
	v_writelane_b32 v252, s1, 44
	s_add_u32 s0, s88, 0x1200
	s_addc_u32 s1, s89, 0
	v_writelane_b32 v252, s0, 45
	s_mov_b32 s64, 0x800000
	s_mov_b32 s65, 0x3f317217
	v_writelane_b32 v252, s1, 46
	s_add_u32 s0, s88, 0x1400
	s_addc_u32 s1, s89, 0
	v_writelane_b32 v252, s0, 47
	v_readlane_b32 s62, v251, 49
	v_readlane_b32 s67, v251, 54
	v_writelane_b32 v252, s1, 48
	s_add_u32 s0, s88, 0x1500
	s_addc_u32 s1, s89, 0
	v_writelane_b32 v252, s0, 49
	s_nop 1
	v_writelane_b32 v252, s1, 50
	s_add_u32 s0, s88, 0x1600
	s_addc_u32 s1, s89, 0
	v_writelane_b32 v252, s0, 51
	s_nop 1
	v_writelane_b32 v252, s1, 52
	s_add_u32 s0, s88, 0x1700
	s_addc_u32 s1, s89, 0
	v_writelane_b32 v252, s0, 53
	s_nop 1
	v_writelane_b32 v252, s1, 54
	s_add_u32 s0, s88, 0x1800
	s_addc_u32 s1, s89, 0
	v_writelane_b32 v252, s0, 55
	s_nop 1
	v_writelane_b32 v252, s1, 56
	s_add_u32 s0, s88, 0x1900
	s_addc_u32 s1, s89, 0
	v_writelane_b32 v252, s0, 57
	s_nop 1
	v_writelane_b32 v252, s1, 58
	s_add_u32 s0, s88, 0x1a00
	s_addc_u32 s1, s89, 0
	v_writelane_b32 v252, s0, 59
	s_nop 1
	v_writelane_b32 v252, s1, 60
	s_add_u32 s0, s88, 0x1b00
	s_addc_u32 s1, s89, 0
	v_writelane_b32 v252, s0, 61
	s_nop 1
	v_writelane_b32 v252, s1, 62
	s_add_u32 s0, s88, 0x1c00
	s_addc_u32 s1, s89, 0
	v_writelane_b32 v252, s0, 63
	s_nop 1
	v_writelane_b32 v253, s1, 0
	s_add_u32 s0, s88, 0x1d00
	s_addc_u32 s1, s89, 0
	v_writelane_b32 v253, s0, 1
	s_nop 1
	v_writelane_b32 v253, s1, 2
	s_add_u32 s0, s88, 0x1e00
	s_addc_u32 s1, s89, 0
	v_writelane_b32 v253, s0, 3
	s_nop 1
	v_writelane_b32 v253, s1, 4
	s_add_u32 s0, s88, 0x1f00
	s_addc_u32 s1, s89, 0
	v_writelane_b32 v253, s0, 5
	s_nop 1
	v_writelane_b32 v253, s1, 6
	s_add_u32 s0, s88, 0x2000
	s_addc_u32 s1, s89, 0
	v_writelane_b32 v253, s0, 7
	s_nop 1
	v_writelane_b32 v253, s1, 8
	s_add_u32 s0, s88, 0x2100
	s_addc_u32 s1, s89, 0
	v_writelane_b32 v253, s0, 9
	s_nop 1
	v_writelane_b32 v253, s1, 10
	s_add_u32 s0, s88, 0x2200
	s_addc_u32 s1, s89, 0
	v_writelane_b32 v253, s0, 11
	s_nop 1
	v_writelane_b32 v253, s1, 12
	s_add_u32 s0, s88, 0x2300
	s_addc_u32 s1, s89, 0
	v_writelane_b32 v253, s0, 13
	s_cmp_eq_u32 s25, 15
	s_nop 0
	v_writelane_b32 v253, s1, 14
	s_cselect_b64 s[0:1], -1, 0
	v_writelane_b32 v253, s0, 15
	s_cmp_eq_u32 s25, 14
	s_nop 0
	v_writelane_b32 v253, s1, 16
	s_cselect_b64 s[0:1], -1, 0
	v_writelane_b32 v253, s0, 17
	s_cmp_eq_u32 s25, 13
	s_nop 0
	v_writelane_b32 v253, s1, 18
	s_cselect_b64 s[0:1], -1, 0
	v_writelane_b32 v253, s0, 19
	s_cmp_eq_u32 s25, 12
	s_nop 0
	v_writelane_b32 v253, s1, 20
	s_cselect_b64 s[0:1], -1, 0
	v_writelane_b32 v253, s0, 21
	s_cmp_eq_u32 s25, 11
	s_nop 0
	v_writelane_b32 v253, s1, 22
	s_cselect_b64 s[0:1], -1, 0
	v_writelane_b32 v253, s0, 23
	s_cmp_eq_u32 s25, 10
	s_nop 0
	v_writelane_b32 v253, s1, 24
	s_cselect_b64 s[0:1], -1, 0
	v_writelane_b32 v253, s0, 25
	s_cmp_eq_u32 s25, 9
	s_nop 0
	v_writelane_b32 v253, s1, 26
	s_cselect_b64 s[0:1], -1, 0
	v_writelane_b32 v253, s0, 27
	s_cmp_eq_u32 s25, 8
	s_nop 0
	v_writelane_b32 v253, s1, 28
	s_cselect_b64 s[0:1], -1, 0
	v_writelane_b32 v253, s0, 29
	s_cmp_eq_u32 s25, 7
	s_nop 0
	v_writelane_b32 v253, s1, 30
	s_cselect_b64 s[0:1], -1, 0
	v_writelane_b32 v253, s0, 31
	s_cmp_eq_u32 s25, 6
	s_nop 0
	v_writelane_b32 v253, s1, 32
	s_cselect_b64 s[0:1], -1, 0
	v_writelane_b32 v253, s0, 33
	s_cmp_eq_u32 s25, 5
	s_nop 0
	v_writelane_b32 v253, s1, 34
	s_cselect_b64 s[0:1], -1, 0
	v_writelane_b32 v253, s0, 35
	s_cmp_eq_u32 s25, 4
	s_nop 0
	v_writelane_b32 v253, s1, 36
	s_cselect_b64 s[0:1], -1, 0
	v_writelane_b32 v253, s0, 37
	s_cmp_eq_u32 s25, 3
	s_nop 0
	v_writelane_b32 v253, s1, 38
	s_cselect_b64 s[0:1], -1, 0
	v_writelane_b32 v253, s0, 39
	s_cmp_eq_u32 s25, 2
	s_nop 0
	v_writelane_b32 v253, s1, 40
	s_cselect_b64 s[0:1], -1, 0
	v_writelane_b32 v253, s0, 41
	s_cmp_eq_u32 s25, 1
	s_nop 0
	v_writelane_b32 v253, s1, 42
	s_cselect_b64 s[0:1], -1, 0
	v_writelane_b32 v253, s0, 43
	s_cmp_eq_u32 s25, 0
	s_nop 0
	v_writelane_b32 v253, s1, 44
	s_cselect_b64 s[0:1], -1, 0
	v_writelane_b32 v253, s0, 45
	s_nop 1
	v_writelane_b32 v253, s1, 46
	s_lshl_b32 s0, s25, 8
	s_add_u32 s0, s2, s0
	s_addc_u32 s1, s3, 0
	s_add_u32 s2, s0, 0x1400
	s_addc_u32 s3, s1, 0
	v_writelane_b32 v253, s2, 47
	s_add_u32 s0, s0, 0x2400
	s_addc_u32 s1, s1, 0
	v_writelane_b32 v253, s3, 48
	v_writelane_b32 v253, s0, 49
	s_nop 1
	v_writelane_b32 v253, s1, 50
	s_movk_i32 s0, 0x3ff
	v_and_or_b32 v0, v0, s0, v206
	s_add_u32 s0, s88, 0x4400
	s_addc_u32 s1, s89, 0
	v_writelane_b32 v253, s0, 51
	s_nop 1
	v_writelane_b32 v253, s1, 52
	s_add_u32 s0, s88, 0x4500
	s_addc_u32 s1, s89, 0
	v_writelane_b32 v253, s0, 53
	s_nop 1
	v_writelane_b32 v253, s1, 54
	s_and_b32 s0, s98, 7
	s_cmp_eq_u32 s0, 0
	s_cselect_b64 s[0:1], -1, 0
	s_abs_i32 s33, s98
	v_cvt_f32_u32_e32 v1, s33
	v_writelane_b32 v253, s0, 55
	v_rcp_iflag_f32_e32 v1, v1
	s_nop 0
	v_writelane_b32 v253, s1, 56
	s_sub_i32 s0, 0, s33
	v_mul_f32_e32 v1, 0x4f7ffffe, v1
	v_cvt_u32_f32_e32 v1, v1
	s_nop 0
	v_readfirstlane_b32 s1, v1
	s_mul_i32 s0, s0, s1
	s_mul_hi_u32 s0, s1, s0
	s_add_i32 s94, s1, s0
	s_mul_i32 s0, s10, s99
	s_mul_i32 s0, s0, s98
	v_writelane_b32 v253, s0, 57
	s_lshr_b32 s0, s98, 3
	v_writelane_b32 v253, s0, 58
	s_add_u32 s0, s88, 0x1e500080
	v_writelane_b32 v253, s0, 59
	s_addc_u32 s0, s89, 0
	v_writelane_b32 v253, s0, 60
	s_add_u32 s0, s88, 0x61280
	s_addc_u32 s1, s89, 0
	v_writelane_b32 v253, s0, 61
	s_add_i32 s63, 0, 0x2004c
	v_mov_b32_e32 v1, 0
	v_writelane_b32 v253, s1, 62
	s_add_i32 s0, 0, 0x20050
	v_writelane_b32 v253, s0, 63
	s_add_i32 s0, 0, 0x20048
	v_writelane_b32 v254, s0, 0
	s_add_i32 s0, 0, 0x20000
	v_writelane_b32 v254, s0, 1
	s_add_i32 s0, 0, 0x20040
	v_writelane_b32 v254, s0, 2
	s_add_i32 s0, 0, 0x20044
	v_writelane_b32 v254, s0, 3
	v_cmp_eq_u32_e64 s[0:1], 0, v0
	s_movk_i32 s99, 0x2000
	s_nop 0
	v_writelane_b32 v254, s0, 4
	s_nop 1
	v_writelane_b32 v254, s1, 5
	v_writelane_b32 v254, s26, 6
	s_nop 1
	v_writelane_b32 v254, s27, 7
	v_writelane_b32 v254, s25, 8
	v_writelane_b32 v254, s28, 9
	s_nop 1
	v_writelane_b32 v254, s29, 10
	v_writelane_b32 v254, s36, 11
	s_nop 1
	v_writelane_b32 v254, s37, 12
	v_writelane_b32 v254, s38, 13
	v_writelane_b32 v254, s39, 14
	v_writelane_b32 v254, s40, 15
	v_writelane_b32 v254, s41, 16
	v_writelane_b32 v254, s42, 17
	v_writelane_b32 v254, s43, 18
	v_writelane_b32 v254, s44, 19
	v_writelane_b32 v254, s45, 20
	v_writelane_b32 v254, s46, 21
	v_writelane_b32 v254, s47, 22
	v_writelane_b32 v254, s48, 23
	v_writelane_b32 v254, s49, 24
	v_writelane_b32 v254, s50, 25
	v_writelane_b32 v254, s51, 26
	v_writelane_b32 v254, s30, 27
	s_nop 1
	v_writelane_b32 v254, s31, 28
	v_writelane_b32 v254, s34, 29
	s_nop 1
	v_writelane_b32 v254, s35, 30
	v_writelane_b32 v254, s57, 31
	v_writelane_b32 v254, s58, 32
	v_writelane_b32 v254, s63, 33
	v_writelane_b32 v254, s88, 34
	s_nop 1
	v_writelane_b32 v254, s89, 35
	v_writelane_b32 v254, s96, 36
	s_nop 1
	v_writelane_b32 v254, s97, 37
	v_writelane_b32 v254, s13, 38
	v_writelane_b32 v254, s94, 39
	s_branch .LBB0_12

.LBB0_39:
	s_or_b64 exec, exec, s[30:31]
	s_add_i32 s29, s41, s34
	s_min_i32 s48, s29, s67
	s_cmp_ge_i32 s92, s48
	s_cbranch_scc1 .LBB0_36
	v_mad_i64_i32 v[66:67], s[30:31], v88, s85, 0
	v_mad_i64_i32 v[68:69], s[30:31], v89, s85, 0
	s_ashr_i32 s29, s28, 31
	s_lshl_b64 s[30:31], s[28:29], 2
	s_sub_i32 s29, s40, s34
	s_add_i32 s49, s42, s34
	v_and_b32_e32 v0, 7, v0
	s_lshl_b32 s34, s92, 1
	v_lshlrev_b32_e32 v0, 4, v0
	s_add_u32 s34, s45, s34
	v_lshl_add_u64 v[68:69], v[68:69], 0, v[0:1]
	s_addc_u32 s35, s46, 0
	v_lshl_add_u64 v[66:67], v[66:67], 0, v[0:1]
	v_lshl_add_u64 v[158:159], s[34:35], 0, v[68:69]
	v_lshl_add_u64 v[160:161], s[34:35], 0, v[66:67]
	s_lshl_b64 s[34:35], s[92:93], 2
	s_add_u32 s30, s30, s34
	s_addc_u32 s31, s31, s35
	v_lshl_add_u64 v[154:155], v[82:83], 1, s[26:27]
	v_lshl_add_u64 v[156:157], v[84:85], 1, s[26:27]
	v_add_u32_e32 v175, 64, v87
	v_add_u32_e32 v176, 64, v86
	v_lshl_add_u64 v[162:163], v[150:151], 0, s[30:31]
	s_mov_b32 s50, 0
	v_xor_b32_e32 v230, 0x80000000, v169
	v_mov_b32_e32 v231, v230
	v_mov_b32_e32 v232, v230
	v_mov_b32_e32 v233, v230
	v_mov_b32_e32 v234, v230
	v_mov_b32_e32 v235, v230
	v_mov_b32_e32 v236, v230
	v_mov_b32_e32 v237, v230
	v_mov_b32_e32 v238, v230
	v_mov_b32_e32 v239, v230
	v_mov_b32_e32 v240, v230
	v_mov_b32_e32 v241, v230
	v_mov_b32_e32 v242, v230
	v_mov_b32_e32 v243, v230
	v_mov_b32_e32 v244, v230
	v_mov_b32_e32 v245, v230

.LBB0_43:
	s_cmp_le_i32 s51, s29
	s_cselect_b64 s[52:53], -1, 0
	s_cmp_ge_i32 s92, s49
	s_cselect_b64 s[54:55], -1, 0
	s_or_b64 s[52:53], s[54:55], s[52:53]
	s_and_b64 vcc, exec, s[52:53]
	s_cbranch_vccnz .LBB0_46
	s_mul_i32 s52, s50, 0xac00
	s_add_i32 s52, s52, 0
	v_add_u32_e32 v177, s52, v166
	ds_read_b128 v[178:181], v177
	ds_read_b128 v[182:185], v177 offset:32
	ds_read_b128 v[186:189], v177 offset:64
	s_waitcnt lgkmcnt(2)
	v_mfma_f32_32x32x16_bf16 v[82:97], v[178:181], v[98:101], v[230:245]
	ds_read_b128 v[178:181], v177 offset:96
	s_waitcnt lgkmcnt(2)
	v_mfma_f32_32x32x16_bf16 v[82:97], v[182:185], v[102:105], v[82:97]
	ds_read_b128 v[182:185], v177 offset:128
	s_waitcnt lgkmcnt(2)
	v_mfma_f32_32x32x16_bf16 v[82:97], v[186:189], v[106:109], v[82:97]
	ds_read_b128 v[186:189], v177 offset:160
	s_waitcnt lgkmcnt(2)
	v_mfma_f32_32x32x16_bf16 v[82:97], v[178:181], v[110:113], v[82:97]
	ds_read_b128 v[178:181], v177 offset:192
	ds_read_b128 v[190:193], v177 offset:224
	s_waitcnt lgkmcnt(3)
	v_mfma_f32_32x32x16_bf16 v[82:97], v[182:185], v[114:117], v[82:97]
	global_load_dwordx4 v[182:185], v[162:163], off offset:-128
	ds_read_b128 v[194:197], v177 offset:8704
	s_waitcnt lgkmcnt(3)
	v_mfma_f32_32x32x16_bf16 v[82:97], v[186:189], v[118:121], v[82:97]
	global_load_dwordx4 v[186:189], v[162:163], off offset:-112
	s_waitcnt lgkmcnt(2)
	v_mfma_f32_32x32x16_bf16 v[82:97], v[178:181], v[122:125], v[82:97]
	global_load_dwordx4 v[178:181], v[162:163], off offset:-64
	global_load_dwordx4 v[198:201], v[162:163], off offset:-48
	ds_read_b128 v[202:205], v177 offset:8736
	global_load_dwordx4 v[218:221], v[162:163], off
	ds_read_b128 v[214:217], v177 offset:8768
	s_waitcnt lgkmcnt(3)
	v_mfma_f32_32x32x16_bf16 v[82:97], v[190:193], v[126:129], v[82:97]
	v_add3_u32 v228, s52, v167, v165
	ds_read_b128 v[190:193], v177 offset:8800
	s_waitcnt lgkmcnt(3)
	v_mfma_f32_32x32x16_bf16 v[66:81], v[194:197], v[98:101], v[230:245]
	s_waitcnt vmcnt(4)
	s_nop 6
	v_add_f32_e32 v0, v182, v82
	v_add_f32_e32 v82, v183, v83
	v_exp_f32_e32 v83, v0
	v_exp_f32_e32 v182, v82
	v_max_f32_e32 v226, v0, v82
	v_add_f32_e32 v183, v83, v182
	v_cvt_pk_bf16_f32 v82, v83, v182
	ds_read_b128 v[194:197], v177 offset:8832
	s_waitcnt lgkmcnt(3)
	v_mfma_f32_32x32x16_bf16 v[66:81], v[202:205], v[102:105], v[66:81]
	v_add_f32_e32 v83, v184, v84
	v_add_f32_e32 v84, v185, v85
	global_load_dwordx4 v[202:205], v[162:163], off offset:16
	v_exp_f32_e32 v182, v83
	v_exp_f32_e32 v0, v84
	v_max_f32_e32 v83, v83, v84
	v_max3_f32 v229, v226, s86, v83
	v_pk_add_f32 v[84:85], v[182:183], v[0:1]
	v_cvt_pk_bf16_f32 v83, v182, v0
	v_pk_add_f32 v[226:227], v[84:85], v[84:85] op_sel_hi:[0,1]
	ds_read_b128 v[182:185], v177 offset:8864
	s_waitcnt vmcnt(4)
	v_add_f32_e32 v0, v186, v86
	v_add_f32_e32 v84, v187, v87
	v_exp_f32_e32 v85, v0
	v_exp_f32_e32 v86, v84
	s_waitcnt lgkmcnt(3)
	v_mfma_f32_32x32x16_bf16 v[66:81], v[214:217], v[106:109], v[66:81]
	v_max_f32_e32 v0, v0, v84
	v_add_f32_e32 v87, v85, v86
	v_cvt_pk_bf16_f32 v84, v85, v86
	ds_read_b128 v[214:217], v177 offset:8896
	v_add_f32_e32 v85, v188, v88
	v_add_f32_e32 v88, v189, v89
	global_load_dwordx4 v[186:189], v[162:163], off offset:64
	s_waitcnt lgkmcnt(3)
	v_mfma_f32_32x32x16_bf16 v[66:81], v[190:193], v[110:113], v[66:81]
	v_exp_f32_e32 v86, v85
	v_exp_f32_e32 v226, v88
	v_max_f32_e32 v85, v85, v88
	v_max3_f32 v0, v229, v0, v85
	v_pk_add_f32 v[88:89], v[86:87], v[226:227]
	v_cvt_pk_bf16_f32 v85, v86, v226
	v_pk_add_f32 v[226:227], v[88:89], v[88:89] op_sel_hi:[0,1]
	ds_read_b128 v[86:89], v177 offset:8928
	s_waitcnt lgkmcnt(3)
	v_mfma_f32_32x32x16_bf16 v[66:81], v[194:197], v[114:117], v[66:81]
	s_waitcnt vmcnt(4)
	v_add_f32_e32 v90, v178, v90
	v_add_f32_e32 v91, v179, v91
	v_exp_f32_e32 v178, v91
	ds_read_b128 v[190:193], v228 offset:17408
	v_exp_f32_e32 v177, v90
	v_max_f32_e32 v91, v90, v91
	v_add_f32_e32 v179, v177, v178
	v_cvt_pk_bf16_f32 v90, v177, v178
	s_waitcnt lgkmcnt(3)
	v_mfma_f32_32x32x16_bf16 v[66:81], v[182:185], v[118:121], v[66:81]
	global_load_dwordx4 v[182:185], v[162:163], off offset:80
	v_add_f32_e32 v92, v180, v92
	v_add_f32_e32 v93, v181, v93
	v_exp_f32_e32 v178, v92
	v_exp_f32_e32 v226, v93
	v_max_f32_e32 v92, v92, v93
	v_max3_f32 v0, v0, v91, v92
	v_pk_add_f32 v[92:93], v[178:179], v[226:227]
	v_cvt_pk_bf16_f32 v91, v178, v226
	v_pk_add_f32 v[226:227], v[92:93], v[92:93] op_sel_hi:[0,1]
	ds_read_b128 v[178:181], v228 offset:22016
	s_waitcnt lgkmcnt(3)
	v_mfma_f32_32x32x16_bf16 v[66:81], v[214:217], v[122:125], v[66:81]
	s_waitcnt vmcnt(4)
	v_add_f32_e32 v92, v198, v94
	v_add_f32_e32 v93, v199, v95
	v_exp_f32_e32 v94, v92
	v_exp_f32_e32 v177, v93
	v_max_f32_e32 v93, v92, v93
	v_add_f32_e32 v95, v94, v177
	v_cvt_pk_bf16_f32 v92, v94, v177
	ds_read_b128 v[194:197], v228 offset:26624
	s_waitcnt lgkmcnt(3)
	v_mfma_f32_32x32x16_bf16 v[66:81], v[86:89], v[126:129], v[66:81]
	v_add_f32_e32 v96, v200, v96
	v_add_f32_e32 v97, v201, v97
	v_exp_f32_e32 v94, v96
	v_exp_f32_e32 v226, v97
	v_max_f32_e32 v86, v96, v97
	v_max3_f32 v0, v0, v93, v86
	v_pk_add_f32 v[86:87], v[94:95], v[226:227]
	v_cvt_pk_bf16_f32 v93, v94, v226
	v_pk_add_f32 v[198:199], v[86:87], v[86:87] op_sel_hi:[0,1]
	ds_read_b128 v[86:89], v228 offset:31232
	ds_read_b128 v[94:97], v228 offset:17440
	s_waitcnt lgkmcnt(4)
	v_mfma_f32_32x32x16_bf16 v[50:65], v[190:193], v[82:85], v[50:65]
	s_waitcnt vmcnt(3)
	v_add_f32_e32 v66, v218, v66
	v_add_f32_e32 v67, v219, v67
	v_exp_f32_e32 v177, v66
	v_exp_f32_e32 v190, v67
	v_max_f32_e32 v67, v66, v67
	v_add_f32_e32 v201, v177, v190
	v_cvt_pk_bf16_f32 v66, v177, v190
	ds_read_b128 v[190:193], v228 offset:22048
	s_waitcnt lgkmcnt(4)
	v_mfma_f32_32x32x16_bf16 v[34:49], v[178:181], v[82:85], v[34:49]
	v_add_f32_e32 v68, v220, v68
	v_add_f32_e32 v69, v221, v69
	v_exp_f32_e32 v198, v68
	v_exp_f32_e32 v200, v69
	v_max_f32_e32 v68, v68, v69
	v_max3_f32 v0, v0, v67, v68
	v_pk_add_f32 v[68:69], v[198:199], v[200:201]
	v_cvt_pk_bf16_f32 v67, v198, v200
	v_pk_add_f32 v[198:199], v[68:69], v[68:69] op_sel_hi:[0,1]
	ds_read_b128 v[178:181], v228 offset:26656
	s_waitcnt lgkmcnt(4)
	v_mfma_f32_32x32x16_bf16 v[18:33], v[194:197], v[82:85], v[18:33]
	s_waitcnt vmcnt(2)
	v_add_f32_e32 v68, v202, v70
	v_add_f32_e32 v69, v203, v71
	v_exp_f32_e32 v70, v68
	v_exp_f32_e32 v177, v69
	v_max_f32_e32 v69, v68, v69
	v_add_f32_e32 v71, v70, v177
	v_cvt_pk_bf16_f32 v68, v70, v177
	ds_read_b128 v[194:197], v228 offset:31264
	s_waitcnt lgkmcnt(4)
	v_mfma_f32_32x32x16_bf16 v[2:17], v[86:89], v[82:85], v[2:17]
	v_add_f32_e32 v72, v204, v72
	v_add_f32_e32 v73, v205, v73
	v_exp_f32_e32 v70, v72
	v_exp_f32_e32 v198, v73
	v_max_f32_e32 v72, v72, v73
	v_max3_f32 v0, v0, v69, v72
	v_pk_add_f32 v[72:73], v[70:71], v[198:199]
	s_nop 0
	v_pk_add_f32 v[72:73], v[72:73], v[72:73] op_sel_hi:[0,1]
	v_cvt_pk_bf16_f32 v69, v70, v198
	s_waitcnt lgkmcnt(3)
	v_mfma_f32_32x32x16_bf16 v[50:65], v[94:97], v[90:93], v[50:65]
	s_waitcnt vmcnt(1)
	v_add_f32_e32 v70, v186, v74
	v_add_f32_e32 v71, v187, v75
	v_exp_f32_e32 v72, v70
	v_exp_f32_e32 v74, v71
	v_max_f32_e32 v71, v70, v71
	v_add_f32_e32 v75, v72, v74
	v_cvt_pk_bf16_f32 v70, v72, v74
	v_add_f32_e32 v76, v188, v76
	v_add_f32_e32 v77, v189, v77
	v_exp_f32_e32 v74, v76
	v_exp_f32_e32 v72, v77
	v_max_f32_e32 v76, v76, v77
	v_max3_f32 v0, v0, v71, v76
	ds_read_b128 v[82:85], v228 offset:17472
	v_pk_add_f32 v[76:77], v[74:75], v[72:73]
	v_cvt_pk_bf16_f32 v71, v74, v72
	v_pk_add_f32 v[94:95], v[76:77], v[76:77] op_sel_hi:[0,1]
	ds_read_b128 v[74:77], v228 offset:22080
	s_waitcnt lgkmcnt(4)
	v_mfma_f32_32x32x16_bf16 v[34:49], v[190:193], v[90:93], v[34:49]
	s_waitcnt lgkmcnt(0)
	v_mfma_f32_32x32x16_bf16 v[34:49], v[74:77], v[66:69], v[34:49]
	ds_read_b128 v[74:77], v228 offset:26720
	v_mfma_f32_32x32x16_bf16 v[18:33], v[178:181], v[90:93], v[18:33]
	s_waitcnt vmcnt(0)
	v_add_f32_e32 v72, v182, v78
	v_add_f32_e32 v73, v183, v79
	v_exp_f32_e32 v78, v72
	v_exp_f32_e32 v86, v73
	v_max_f32_e32 v177, v72, v73
	v_add_f32_e32 v79, v78, v86
	v_cvt_pk_bf16_f32 v72, v78, v86
	v_add_f32_e32 v73, v184, v80
	v_add_f32_e32 v80, v185, v81
	v_exp_f32_e32 v78, v73
	v_exp_f32_e32 v94, v80
	ds_read_b128 v[86:89], v228 offset:26688
	v_max_f32_e32 v178, v73, v80
	v_pk_add_f32 v[96:97], v[78:79], v[94:95]
	v_cvt_pk_bf16_f32 v73, v78, v94
	ds_read_b128 v[78:81], v228 offset:17504
	v_mfma_f32_32x32x16_bf16 v[50:65], v[82:85], v[66:69], v[50:65]
	ds_read_b128 v[82:85], v228 offset:31296
	v_mfma_f32_32x32x16_bf16 v[2:17], v[194:197], v[90:93], v[2:17]
	ds_read_b128 v[90:93], v228 offset:22112
	s_waitcnt lgkmcnt(3)
	v_mfma_f32_32x32x16_bf16 v[18:33], v[86:89], v[66:69], v[18:33]
	ds_read_b128 v[86:89], v228 offset:31328
	s_waitcnt lgkmcnt(2)
	v_mfma_f32_32x32x16_bf16 v[2:17], v[82:85], v[66:69], v[2:17]
	v_mfma_f32_32x32x16_bf16 v[50:65], v[78:81], v[70:73], v[50:65]
	s_waitcnt lgkmcnt(1)
	v_mfma_f32_32x32x16_bf16 v[34:49], v[90:93], v[70:73], v[34:49]
	v_mfma_f32_32x32x16_bf16 v[18:33], v[74:77], v[70:73], v[18:33]
	s_waitcnt lgkmcnt(0)
	v_mfma_f32_32x32x16_bf16 v[2:17], v[86:89], v[70:73], v[2:17]
	v_and_b32_e32 v67, 64, v210
	v_xor_b32_e32 v66, 32, v210
	v_add_u32_e32 v67, 64, v67
	v_cmp_lt_i32_e32 vcc, v66, v67
	v_max3_f32 v0, v0, v177, v178
	v_add_f32_e32 v67, v96, v97
	v_cndmask_b32_e32 v66, v210, v66, vcc
	v_lshlrev_b32_e32 v66, 2, v66
	ds_bpermute_b32 v66, v66, v0
	v_add_f32_e32 v168, v168, v67
	s_waitcnt lgkmcnt(0)
	v_max_f32_e32 v66, v66, v66
	v_max_f32_e32 v0, v0, v66
	v_cmp_lt_f32_e32 vcc, s87, v0
	s_cbranch_vccz .LBB0_46
	v_max_f32_e32 v0, v0, v0
	v_max_f32_e32 v66, 0, v0
	v_exp_f32_e64 v0, -v66
	v_add_f32_e32 v169, v169, v66
	v_xor_b32_e32 v230, 0x80000000, v169
	v_mov_b32_e32 v231, v230
	v_mov_b32_e32 v232, v230
	v_mov_b32_e32 v233, v230
	v_mov_b32_e32 v234, v230
	v_mov_b32_e32 v235, v230
	v_mov_b32_e32 v236, v230
	v_mov_b32_e32 v237, v230
	v_mov_b32_e32 v238, v230
	v_mov_b32_e32 v239, v230
	v_mov_b32_e32 v240, v230
	v_mov_b32_e32 v241, v230
	v_mov_b32_e32 v242, v230
	v_mov_b32_e32 v243, v230
	v_mov_b32_e32 v244, v230
	v_mov_b32_e32 v245, v230
	v_mul_f32_e32 v168, v168, v0
	v_pk_mul_f32 v[64:65], v[64:65], v[0:1] op_sel_hi:[1,0]
	v_pk_mul_f32 v[62:63], v[62:63], v[0:1] op_sel_hi:[1,0]
	v_pk_mul_f32 v[60:61], v[60:61], v[0:1] op_sel_hi:[1,0]
	v_pk_mul_f32 v[58:59], v[58:59], v[0:1] op_sel_hi:[1,0]
	v_pk_mul_f32 v[56:57], v[56:57], v[0:1] op_sel_hi:[1,0]
	v_pk_mul_f32 v[54:55], v[54:55], v[0:1] op_sel_hi:[1,0]
	v_pk_mul_f32 v[52:53], v[52:53], v[0:1] op_sel_hi:[1,0]
	v_pk_mul_f32 v[50:51], v[50:51], v[0:1] op_sel_hi:[1,0]
	v_pk_mul_f32 v[48:49], v[48:49], v[0:1] op_sel_hi:[1,0]
	v_pk_mul_f32 v[46:47], v[46:47], v[0:1] op_sel_hi:[1,0]
	v_pk_mul_f32 v[44:45], v[44:45], v[0:1] op_sel_hi:[1,0]
	v_pk_mul_f32 v[42:43], v[42:43], v[0:1] op_sel_hi:[1,0]
	v_pk_mul_f32 v[40:41], v[40:41], v[0:1] op_sel_hi:[1,0]
	v_pk_mul_f32 v[38:39], v[38:39], v[0:1] op_sel_hi:[1,0]
	v_pk_mul_f32 v[36:37], v[36:37], v[0:1] op_sel_hi:[1,0]
	v_pk_mul_f32 v[34:35], v[34:35], v[0:1] op_sel_hi:[1,0]
	v_pk_mul_f32 v[32:33], v[32:33], v[0:1] op_sel_hi:[1,0]
	v_pk_mul_f32 v[30:31], v[30:31], v[0:1] op_sel_hi:[1,0]
	v_pk_mul_f32 v[28:29], v[28:29], v[0:1] op_sel_hi:[1,0]
	v_pk_mul_f32 v[26:27], v[26:27], v[0:1] op_sel_hi:[1,0]
	v_pk_mul_f32 v[24:25], v[24:25], v[0:1] op_sel_hi:[1,0]
	v_pk_mul_f32 v[22:23], v[22:23], v[0:1] op_sel_hi:[1,0]
	v_pk_mul_f32 v[20:21], v[20:21], v[0:1] op_sel_hi:[1,0]
	v_pk_mul_f32 v[18:19], v[18:19], v[0:1] op_sel_hi:[1,0]
	v_pk_mul_f32 v[16:17], v[16:17], v[0:1] op_sel_hi:[1,0]
	v_pk_mul_f32 v[14:15], v[14:15], v[0:1] op_sel_hi:[1,0]
	v_pk_mul_f32 v[12:13], v[12:13], v[0:1] op_sel_hi:[1,0]
	v_pk_mul_f32 v[10:11], v[10:11], v[0:1] op_sel_hi:[1,0]
	v_pk_mul_f32 v[8:9], v[8:9], v[0:1] op_sel_hi:[1,0]
	v_pk_mul_f32 v[6:7], v[6:7], v[0:1] op_sel_hi:[1,0]
	v_pk_mul_f32 v[4:5], v[4:5], v[0:1] op_sel_hi:[1,0]
	v_pk_mul_f32 v[2:3], v[2:3], v[0:1] op_sel_hi:[1,0]

.LBB0_107:
	s_add_i32 s70, s70, s59
	s_ashr_i32 s1, s70, 31
	v_mov_b32_e32 v8, v222
	s_add_u32 s0, s70, s24
	s_addc_u32 s1, s1, s25
	v_and_b32_e32 v0, 31, v8
	v_lshl_add_u64 v[166:167], s[0:1], 0, v[0:1]
	v_readlane_b32 s0, v251, 61
	v_readlane_b32 s1, v251, 62
	s_movk_i32 s73, 0x600
	v_ashrrev_i32_e32 v180, 5, v8
	v_mov_b64_e32 v[2:3], s[0:1]
	v_mad_u64_u32 v[2:3], s[0:1], v166, s73, v[2:3]
	s_mul_i32 s0, s68, 0xc0
	s_ashr_i32 s1, s0, 31
	v_mad_i32_i24 v3, v167, s73, v3
	s_lshl_b64 s[28:29], s[0:1], 1
	v_lshlrev_b32_e32 v4, 3, v180
	v_lshl_add_u64 v[2:3], v[2:3], 0, s[28:29]
	v_ashrrev_i32_e32 v5, 31, v4
	v_lshl_add_u64 v[2:3], v[4:5], 1, v[2:3]
	v_mov_b32_e32 v42, v223
	s_mov_b32 s40, 0x2aaaaaab
	global_load_dwordx4 v[98:101], v[2:3], off
	global_load_dwordx4 v[102:105], v[2:3], off offset:32
	global_load_dwordx4 v[106:109], v[2:3], off offset:64
	global_load_dwordx4 v[110:113], v[2:3], off offset:96
	global_load_dwordx4 v[114:117], v[2:3], off offset:128
	global_load_dwordx4 v[118:121], v[2:3], off offset:160
	global_load_dwordx4 v[122:125], v[2:3], off offset:192
	global_load_dwordx4 v[126:129], v[2:3], off offset:224
	global_load_dwordx4 v[130:133], v[2:3], off offset:256
	global_load_dwordx4 v[134:137], v[2:3], off offset:288
	global_load_dwordx4 v[138:141], v[2:3], off offset:320
	global_load_dwordx4 v[142:145], v[2:3], off offset:352
	v_mul_hi_i32 v2, v42, s40
	v_lshrrev_b32_e32 v3, 31, v2
	v_ashrrev_i32_e32 v2, 2, v2
	v_add_u32_e32 v41, v2, v3
	v_mul_lo_u32 v2, v41, 24
	v_add_u32_e32 v13, 0x200, v42
	v_sub_u32_e32 v12, v42, v2
	v_mul_hi_i32 v2, v13, s40
	v_lshrrev_b32_e32 v3, 31, v2
	v_ashrrev_i32_e32 v2, 2, v2
	v_add_u32_e32 v40, v2, v3
	v_mul_lo_u32 v2, v40, 24
	s_mul_i32 s72, s24, 0x600
	v_readlane_b32 s0, v251, 63
	v_lshlrev_b32_e32 v4, 1, v8
	v_sub_u32_e32 v14, v13, v2
	v_add_u32_e32 v2, 0x400, v42
	s_mul_hi_i32 s70, s24, 0x600
	v_readlane_b32 s1, v252, 0
	s_add_u32 s0, s0, s72
	v_and_b32_e32 v9, 8, v4
	v_lshrrev_b32_e32 v4, 1, v8
	v_mul_hi_i32 v3, v2, s40
	s_addc_u32 s1, s1, s70
	v_and_b32_e32 v10, 4, v4
	v_lshrrev_b32_e32 v4, 31, v3
	v_ashrrev_i32_e32 v3, 2, v3
	s_add_u32 s34, s0, s28
	v_add_u32_e32 v43, v3, v4
	s_addc_u32 s35, s1, s29
	v_mul_lo_u32 v3, v43, 24
	v_lshlrev_b32_e32 v6, 3, v12
	v_sub_u32_e32 v15, v2, v3
	v_mov_b64_e32 v[2:3], s[34:35]
	v_ashrrev_i32_e32 v7, 31, v6
	v_mad_i64_i32 v[4:5], s[34:35], v41, s73, v[2:3]
	v_lshlrev_b64 v[34:35], 1, v[6:7]
	v_lshlrev_b32_e32 v6, 3, v14
	v_lshl_add_u64 v[4:5], v[4:5], 0, v[34:35]
	v_ashrrev_i32_e32 v7, 31, v6
	global_load_dwordx4 v[146:149], v[4:5], off
	v_mad_i64_i32 v[4:5], s[34:35], v40, s73, v[2:3]
	v_lshlrev_b64 v[36:37], 1, v[6:7]
	v_lshl_add_u64 v[4:5], v[4:5], 0, v[36:37]
	s_lshl_b32 s0, s68, 7
	global_load_dwordx4 v[150:153], v[4:5], off
	v_lshlrev_b32_e32 v4, 3, v15
	s_ashr_i32 s1, s0, 31
	v_readlane_b32 s30, v252, 1
	v_ashrrev_i32_e32 v5, 31, v4
	s_mul_hi_i32 s27, s0, 0xc000
	v_readlane_b32 s31, v252, 2
	s_add_u32 s30, s30, s26
	v_mad_i64_i32 v[2:3], s[34:35], v43, s73, v[2:3]
	v_lshlrev_b64 v[38:39], 1, v[4:5]
	s_addc_u32 s31, s31, s27
	s_lshl_b64 s[24:25], s[24:25], 1
	v_lshl_add_u64 v[2:3], v[2:3], 0, v[38:39]
	s_add_u32 s30, s30, s24
	global_load_dwordx4 v[154:157], v[2:3], off
	v_lshlrev_b32_e32 v2, 4, v42
	s_addc_u32 s31, s31, s25
	v_and_b32_e32 v168, 0x70, v2
	v_mov_b32_e32 v169, v1
	v_lshl_add_u64 v[2:3], s[30:31], 0, v[168:169]
	v_ashrrev_i32_e32 v44, 3, v42
	v_mad_i64_i32 v[4:5], s[30:31], v44, s85, v[2:3]
	v_ashrrev_i32_e32 v45, 3, v13
	global_load_dwordx4 v[158:161], v[4:5], off
	v_mad_i64_i32 v[2:3], s[30:31], v45, s85, v[2:3]
	global_load_dwordx4 v[162:165], v[2:3], off
	s_movk_i32 s31, 0x190
	v_mul_lo_u32 v169, v41, s31
	v_lshlrev_b32_e32 v181, 4, v12
	v_add3_u32 v2, 0, v169, v181
	v_mul_lo_u32 v182, v40, s31
	v_lshlrev_b32_e32 v183, 4, v14
	v_mul_lo_u32 v184, v43, s31
	v_lshlrev_b32_e32 v185, 4, v15
	s_movk_i32 s30, 0x90
	v_mul_lo_u32 v186, v44, s30
	v_mul_lo_u32 v187, v45, s30
	v_and_b32_e32 v11, 19, v8
	v_mul_u32_u24_e32 v190, 0x90, v0
	s_mov_b64 s[34:35], 0x26900080
	s_mov_b32 s40, 0
	s_mov_b32 s41, s40
	s_mov_b32 s42, s40
	s_mov_b32 s43, s40
	s_mov_b32 s44, s40
	s_mov_b32 s45, s40
	s_mov_b32 s46, s40
	s_mov_b32 s47, s40
	s_mov_b32 s48, s40
	s_mov_b32 s49, s40
	s_mov_b32 s50, s40
	s_mov_b32 s51, s40
	s_mov_b32 s52, s40
	s_mov_b32 s53, s40
	s_mov_b32 s54, s40
	s_mov_b32 s55, s40
	s_mov_b32 s30, 64
	v_mov_b32_e32 v193, 0
	s_waitcnt vmcnt(0)
	ds_write_b128 v2, v[146:149]
	v_add3_u32 v2, 0, v182, v183
	s_waitcnt vmcnt(3)
	ds_write_b128 v2, v[150:153]
	v_add3_u32 v2, 0, v184, v185
	s_waitcnt vmcnt(2)
	ds_write_b128 v2, v[154:157]
	v_add_u32_e32 v2, 0, v168
	v_add_u32_e32 v3, v2, v186
	v_add_u32_e32 v2, v2, v187
	s_waitcnt vmcnt(1)
	ds_write_b128 v3, v[158:161] offset:25600
	v_ashrrev_i32_e32 v3, 1, v8
	v_and_b32_e32 v188, -16, v3
	s_waitcnt vmcnt(0)
	ds_write_b128 v2, v[162:165] offset:25600
	v_or3_b32 v2, v11, v9, v10
	v_mad_u32_u24 v189, v2, s31, v188
	v_add_u32_e32 v0, 0, v189
	s_waitcnt lgkmcnt(0)
	s_barrier
	ds_read_b128 v[18:21], v0
	ds_read_b128 v[46:49], v0 offset:32
	s_waitcnt lgkmcnt(1)
	v_mfma_f32_32x32x16_bf16 v[18:33], v[18:21], v[98:101], 0
	s_mov_b32 s31, 0xc2700000
	v_mov_b64_e32 v[2:3], s[40:41]
	v_mov_b64_e32 v[16:17], s[54:55]
	v_mov_b64_e32 v[4:5], s[42:43]
	v_mov_b64_e32 v[6:7], s[44:45]
	v_mov_b64_e32 v[8:9], s[46:47]
	v_mov_b64_e32 v[10:11], s[48:49]
	s_waitcnt lgkmcnt(0)
	v_mfma_f32_32x32x16_bf16 v[18:33], v[46:49], v[102:105], v[18:33]
	ds_read_b128 v[46:49], v0 offset:64
	v_mov_b64_e32 v[12:13], s[50:51]
	v_mov_b64_e32 v[14:15], s[52:53]
	v_mov_b64_e32 v[64:65], v[16:17]
	v_mov_b64_e32 v[62:63], v[14:15]
	v_mov_b64_e32 v[60:61], v[12:13]
	v_mov_b64_e32 v[58:59], v[10:11]
	s_waitcnt lgkmcnt(0)
	v_mfma_f32_32x32x16_bf16 v[18:33], v[46:49], v[106:109], v[18:33]
	ds_read_b128 v[46:49], v0 offset:96
	v_mov_b64_e32 v[56:57], v[8:9]
	v_mov_b64_e32 v[54:55], v[6:7]
	v_mov_b64_e32 v[52:53], v[4:5]
	v_mov_b64_e32 v[50:51], v[2:3]
	s_waitcnt lgkmcnt(0)
	v_mfma_f32_32x32x16_bf16 v[18:33], v[46:49], v[110:113], v[18:33]
	ds_read_b128 v[46:49], v0 offset:128
	s_waitcnt lgkmcnt(0)
	v_mfma_f32_32x32x16_bf16 v[18:33], v[46:49], v[114:117], v[18:33]
	ds_read_b128 v[46:49], v0 offset:160
	s_waitcnt lgkmcnt(0)
	v_mfma_f32_32x32x16_bf16 v[18:33], v[46:49], v[118:121], v[18:33]
	ds_read_b128 v[46:49], v0 offset:192
	s_waitcnt lgkmcnt(0)
	v_mfma_f32_32x32x16_bf16 v[18:33], v[46:49], v[122:125], v[18:33]
	ds_read_b128 v[46:49], v0 offset:224
	s_waitcnt lgkmcnt(0)
	v_mfma_f32_32x32x16_bf16 v[18:33], v[46:49], v[126:129], v[18:33]
	ds_read_b128 v[46:49], v0 offset:256
	s_waitcnt lgkmcnt(0)
	v_mfma_f32_32x32x16_bf16 v[18:33], v[46:49], v[130:133], v[18:33]
	ds_read_b128 v[46:49], v0 offset:288
	s_waitcnt lgkmcnt(0)
	v_mfma_f32_32x32x16_bf16 v[18:33], v[46:49], v[134:137], v[18:33]
	ds_read_b128 v[46:49], v0 offset:320
	s_waitcnt lgkmcnt(0)
	v_mfma_f32_32x32x16_bf16 v[18:33], v[46:49], v[138:141], v[18:33]
	ds_read_b128 v[46:49], v0 offset:352
	s_waitcnt lgkmcnt(0)
	v_mfma_f32_32x32x16_bf16 v[18:33], v[46:49], v[142:145], v[18:33]
	s_nop 11
	v_max_f32_e32 v0, v18, v19
	v_max3_f32 v0, v0, v20, v21
	v_max3_f32 v0, v0, v22, v23
	v_max3_f32 v0, v0, v24, v25
	v_and_b32_e32 v19, 64, v210
	v_max3_f32 v0, v0, v26, v27
	v_xor_b32_e32 v18, 32, v210
	v_add_u32_e32 v19, 64, v19
	v_max3_f32 v0, v0, v28, v29
	v_cmp_lt_i32_e32 vcc, v18, v19
	v_max3_f32 v0, v0, v30, v31
	v_max3_f32 v0, v0, v32, v33
	v_cndmask_b32_e32 v18, v210, v18, vcc
	v_lshlrev_b32_e32 v191, 2, v18
	ds_bpermute_b32 v18, v191, v0
	s_waitcnt lgkmcnt(0)
	v_max3_f32 v192, v0, v18, s31
	v_mov_b64_e32 v[18:19], s[26:27]
	v_and_b32_e32 v0, 7, v42
	v_mad_i64_i32 v[20:21], s[26:27], v45, s85, v[18:19]
	v_lshlrev_b32_e32 v0, 4, v0
	v_mad_i64_i32 v[18:19], s[26:27], v44, s85, v[18:19]
	v_lshl_add_u64 v[20:21], v[20:21], 0, v[0:1]
	v_lshl_add_u64 v[18:19], v[18:19], 0, v[0:1]
	v_lshl_add_u64 v[20:21], v[20:21], 0, s[24:25]
	v_lshl_add_u64 v[18:19], v[18:19], 0, s[24:25]
	s_add_u32 s24, s28, s72
	s_addc_u32 s25, s29, s70
	v_lshl_add_u64 v[172:173], v[18:19], 0, s[34:35]
	v_mov_b64_e32 v[18:19], s[24:25]
	v_lshl_add_u64 v[170:171], v[20:21], 0, s[34:35]
	v_mad_i64_i32 v[20:21], s[24:25], v41, s73, v[18:19]
	v_lshl_add_u64 v[20:21], v[20:21], 0, v[34:35]
	s_mov_b64 s[26:27], 0x24518000
	v_lshl_add_u64 v[174:175], v[20:21], 0, s[26:27]
	v_mad_i64_i32 v[20:21], s[24:25], v40, s73, v[18:19]
	v_mad_i64_i32 v[18:19], s[24:25], v43, s73, v[18:19]
	v_lshl_add_u64 v[20:21], v[20:21], 0, v[36:37]
	v_lshl_add_u64 v[18:19], v[18:19], 0, v[38:39]
	v_lshl_add_u64 v[176:177], v[20:21], 0, s[26:27]
	v_lshl_add_u64 v[178:179], v[18:19], 0, s[26:27]
	v_mov_b64_e32 v[48:49], v[16:17]
	v_mov_b64_e32 v[32:33], v[16:17]
	v_mov_b64_e32 v[46:47], v[14:15]
	v_mov_b64_e32 v[44:45], v[12:13]
	v_mov_b64_e32 v[42:43], v[10:11]
	v_mov_b64_e32 v[40:41], v[8:9]
	v_mov_b64_e32 v[38:39], v[6:7]
	v_mov_b64_e32 v[36:37], v[4:5]
	v_mov_b64_e32 v[34:35], v[2:3]
	v_mov_b64_e32 v[30:31], v[14:15]
	v_mov_b64_e32 v[28:29], v[12:13]
	v_mov_b64_e32 v[26:27], v[10:11]
	v_mov_b64_e32 v[24:25], v[8:9]
	v_mov_b64_e32 v[22:23], v[6:7]
	v_mov_b64_e32 v[20:21], v[4:5]
	v_mov_b64_e32 v[18:19], v[2:3]
	s_mov_b64 s[34:35], 0x18000
	v_xor_b32_e32 v228, 0x80000000, v192
	v_mov_b32_e32 v229, v228
	v_mov_b32_e32 v230, v228
	v_mov_b32_e32 v231, v228
	v_mov_b32_e32 v232, v228
	v_mov_b32_e32 v233, v228
	v_mov_b32_e32 v234, v228
	v_mov_b32_e32 v235, v228
	v_mov_b32_e32 v236, v228
	v_mov_b32_e32 v237, v228
	v_mov_b32_e32 v238, v228
	v_mov_b32_e32 v239, v228
	v_mov_b32_e32 v240, v228
	v_mov_b32_e32 v241, v228
	v_mov_b32_e32 v242, v228
	v_mov_b32_e32 v243, v228
	s_branch .LBB0_109

.LBB0_111:
	s_mul_i32 s28, s40, 0xac00
	s_add_i32 s28, s28, 0
	v_add_u32_e32 v220, s28, v189
	ds_read_b128 v[194:197], v220
	ds_read_b128 v[198:201], v220 offset:32
	ds_read_b128 v[202:205], v220 offset:64
	s_waitcnt lgkmcnt(2)
	v_mfma_f32_32x32x16_bf16 v[82:97], v[194:197], v[98:101], v[228:243]
	ds_read_b128 v[194:197], v220 offset:96
	s_waitcnt lgkmcnt(2)
	v_mfma_f32_32x32x16_bf16 v[82:97], v[198:201], v[102:105], v[82:97]
	ds_read_b128 v[198:201], v220 offset:128
	s_waitcnt lgkmcnt(2)
	v_mfma_f32_32x32x16_bf16 v[82:97], v[202:205], v[106:109], v[82:97]
	ds_read_b128 v[202:205], v220 offset:160
	s_waitcnt lgkmcnt(2)
	v_mfma_f32_32x32x16_bf16 v[82:97], v[194:197], v[110:113], v[82:97]
	ds_read_b128 v[194:197], v220 offset:192
	s_waitcnt lgkmcnt(2)
	v_mfma_f32_32x32x16_bf16 v[82:97], v[198:201], v[114:117], v[82:97]
	ds_read_b128 v[198:201], v220 offset:224
	s_waitcnt lgkmcnt(2)
	v_mfma_f32_32x32x16_bf16 v[82:97], v[202:205], v[118:121], v[82:97]
	ds_read_b128 v[202:205], v220 offset:256
	s_waitcnt lgkmcnt(2)
	v_mfma_f32_32x32x16_bf16 v[82:97], v[194:197], v[122:125], v[82:97]
	ds_read_b128 v[194:197], v220 offset:288
	s_waitcnt lgkmcnt(2)
	v_mfma_f32_32x32x16_bf16 v[82:97], v[198:201], v[126:129], v[82:97]
	ds_read_b128 v[198:201], v220 offset:320
	s_waitcnt lgkmcnt(2)
	v_mfma_f32_32x32x16_bf16 v[82:97], v[202:205], v[130:133], v[82:97]
	ds_read_b128 v[202:205], v220 offset:352
	s_waitcnt lgkmcnt(2)
	v_mfma_f32_32x32x16_bf16 v[82:97], v[194:197], v[134:137], v[82:97]
	ds_read_b128 v[194:197], v220 offset:12800
	s_waitcnt lgkmcnt(2)
	v_mfma_f32_32x32x16_bf16 v[82:97], v[198:201], v[138:141], v[82:97]
	ds_read_b128 v[198:201], v220 offset:12832
	s_waitcnt lgkmcnt(2)
	v_mfma_f32_32x32x16_bf16 v[82:97], v[202:205], v[142:145], v[82:97]
	ds_read_b128 v[202:205], v220 offset:12864
	v_add3_u32 v221, s28, v190, v188
	s_waitcnt lgkmcnt(2)
	v_mfma_f32_32x32x16_bf16 v[66:81], v[194:197], v[98:101], v[228:243]
	ds_read_b128 v[194:197], v220 offset:12896
	ds_read_b128 v[214:217], v220 offset:12928
	s_waitcnt lgkmcnt(3)
	v_mfma_f32_32x32x16_bf16 v[66:81], v[198:201], v[102:105], v[66:81]
	s_nop 3
	v_exp_f32_e32 v0, v82
	v_exp_f32_e32 v198, v83
	v_max_f32_e32 v83, v82, v83
	v_add_f32_e32 v219, v0, v198
	v_cvt_pk_bf16_f32 v82, v0, v198
	s_waitcnt lgkmcnt(2)
	v_mfma_f32_32x32x16_bf16 v[66:81], v[202:205], v[106:109], v[66:81]
	ds_read_b128 v[198:201], v220 offset:12960
	v_exp_f32_e32 v218, v84
	v_exp_f32_e32 v0, v85
	v_max_f32_e32 v84, v84, v85
	v_max3_f32 v226, v83, s86, v84
	v_pk_add_f32 v[84:85], v[218:219], v[0:1]
	v_cvt_pk_bf16_f32 v83, v218, v0
	v_pk_add_f32 v[218:219], v[84:85], v[84:85] op_sel_hi:[0,1]
	s_waitcnt lgkmcnt(2)
	v_mfma_f32_32x32x16_bf16 v[66:81], v[194:197], v[110:113], v[66:81]
	ds_read_b128 v[194:197], v220 offset:12992
	ds_read_b128 v[202:205], v220 offset:13024
	s_waitcnt lgkmcnt(3)
	v_mfma_f32_32x32x16_bf16 v[66:81], v[214:217], v[114:117], v[66:81]
	v_exp_f32_e32 v0, v86
	v_exp_f32_e32 v84, v87
	v_max_f32_e32 v85, v86, v87
	v_add_f32_e32 v87, v0, v84
	v_cvt_pk_bf16_f32 v84, v0, v84
	s_waitcnt lgkmcnt(2)
	v_mfma_f32_32x32x16_bf16 v[66:81], v[198:201], v[118:121], v[66:81]
	ds_read_b128 v[214:217], v220 offset:13056
	v_exp_f32_e32 v86, v88
	v_exp_f32_e32 v218, v89
	v_max_f32_e32 v0, v88, v89
	v_pk_add_f32 v[88:89], v[86:87], v[218:219]
	v_max3_f32 v0, v226, v85, v0
	v_cvt_pk_bf16_f32 v85, v86, v218
	v_pk_add_f32 v[218:219], v[88:89], v[88:89] op_sel_hi:[0,1]
	s_waitcnt lgkmcnt(2)
	v_mfma_f32_32x32x16_bf16 v[66:81], v[194:197], v[122:125], v[66:81]
	ds_read_b128 v[86:89], v220 offset:13088
	ds_read_b128 v[194:197], v220 offset:13120
	s_waitcnt lgkmcnt(3)
	v_mfma_f32_32x32x16_bf16 v[66:81], v[202:205], v[126:129], v[66:81]
	v_exp_f32_e32 v198, v90
	v_exp_f32_e32 v199, v91
	v_max_f32_e32 v91, v90, v91
	v_add_f32_e32 v203, v198, v199
	v_cvt_pk_bf16_f32 v90, v198, v199
	s_waitcnt lgkmcnt(2)
	v_mfma_f32_32x32x16_bf16 v[66:81], v[214:217], v[130:133], v[66:81]
	ds_read_b128 v[198:201], v220 offset:13152
	v_exp_f32_e32 v202, v92
	v_exp_f32_e32 v218, v93
	v_max_f32_e32 v92, v92, v93
	v_max3_f32 v0, v0, v91, v92
	v_pk_add_f32 v[92:93], v[202:203], v[218:219]
	v_cvt_pk_bf16_f32 v91, v202, v218
	v_pk_add_f32 v[214:215], v[92:93], v[92:93] op_sel_hi:[0,1]
	s_waitcnt lgkmcnt(2)
	v_mfma_f32_32x32x16_bf16 v[66:81], v[86:89], v[134:137], v[66:81]
	ds_read_b128 v[86:89], v221 offset:25600
	ds_read_b128 v[202:205], v221 offset:30208
	s_waitcnt lgkmcnt(3)
	v_mfma_f32_32x32x16_bf16 v[66:81], v[194:197], v[138:141], v[66:81]
	v_exp_f32_e32 v92, v94
	v_exp_f32_e32 v93, v95
	v_max_f32_e32 v216, v94, v95
	v_add_f32_e32 v95, v92, v93
	v_cvt_pk_bf16_f32 v92, v92, v93
	ds_read_b128 v[194:197], v221 offset:34816
	s_waitcnt lgkmcnt(3)
	v_mfma_f32_32x32x16_bf16 v[66:81], v[198:201], v[142:145], v[66:81]
	v_exp_f32_e32 v94, v96
	v_exp_f32_e32 v214, v97
	v_max_f32_e32 v93, v96, v97
	v_pk_add_f32 v[96:97], v[94:95], v[214:215]
	v_max3_f32 v0, v0, v216, v93
	v_cvt_pk_bf16_f32 v93, v94, v214
	v_pk_add_f32 v[214:215], v[96:97], v[96:97] op_sel_hi:[0,1]
	ds_read_b128 v[94:97], v221 offset:39424
	ds_read_b128 v[198:201], v221 offset:25632
	s_waitcnt lgkmcnt(4)
	v_mfma_f32_32x32x16_bf16 v[2:17], v[86:89], v[82:85], v[2:17]
	s_nop 0
	v_exp_f32_e32 v86, v66
	v_exp_f32_e32 v87, v67
	v_max_f32_e32 v67, v66, v67
	v_add_f32_e32 v217, v86, v87
	v_cvt_pk_bf16_f32 v66, v86, v87
	ds_read_b128 v[86:89], v221 offset:30240
	s_waitcnt lgkmcnt(4)
	v_mfma_f32_32x32x16_bf16 v[50:65], v[202:205], v[82:85], v[50:65]
	v_exp_f32_e32 v214, v68
	v_exp_f32_e32 v216, v69
	v_max_f32_e32 v68, v68, v69
	v_max3_f32 v0, v0, v67, v68
	v_pk_add_f32 v[68:69], v[214:215], v[216:217]
	v_cvt_pk_bf16_f32 v67, v214, v216
	v_pk_add_f32 v[218:219], v[68:69], v[68:69] op_sel_hi:[0,1]
	ds_read_b128 v[202:205], v221 offset:34848
	s_waitcnt lgkmcnt(4)
	v_mfma_f32_32x32x16_bf16 v[34:49], v[194:197], v[82:85], v[34:49]
	v_exp_f32_e32 v68, v70
	v_exp_f32_e32 v69, v71
	v_max_f32_e32 v214, v70, v71
	v_add_f32_e32 v71, v68, v69
	v_cvt_pk_bf16_f32 v68, v68, v69
	ds_read_b128 v[194:197], v221 offset:39456
	s_waitcnt lgkmcnt(4)
	v_mfma_f32_32x32x16_bf16 v[18:33], v[94:97], v[82:85], v[18:33]
	v_exp_f32_e32 v70, v72
	v_exp_f32_e32 v218, v73
	v_max_f32_e32 v69, v72, v73
	v_pk_add_f32 v[72:73], v[70:71], v[218:219]
	v_max3_f32 v0, v0, v214, v69
	v_pk_add_f32 v[72:73], v[72:73], v[72:73] op_sel_hi:[0,1]
	v_cvt_pk_bf16_f32 v69, v70, v218
	s_waitcnt lgkmcnt(3)
	v_mfma_f32_32x32x16_bf16 v[2:17], v[198:201], v[90:93], v[2:17]
	v_exp_f32_e32 v70, v74
	v_exp_f32_e32 v71, v75
	v_max_f32_e32 v94, v74, v75
	v_add_f32_e32 v75, v70, v71
	v_cvt_pk_bf16_f32 v70, v70, v71
	v_exp_f32_e32 v74, v76
	v_exp_f32_e32 v72, v77
	v_max_f32_e32 v71, v76, v77
	v_pk_add_f32 v[76:77], v[74:75], v[72:73]
	v_max3_f32 v0, v0, v94, v71
	v_pk_add_f32 v[94:95], v[76:77], v[76:77] op_sel_hi:[0,1]
	v_cvt_pk_bf16_f32 v71, v74, v72
	ds_read_b128 v[74:77], v221 offset:30272
	s_waitcnt lgkmcnt(3)
	v_mfma_f32_32x32x16_bf16 v[50:65], v[86:89], v[90:93], v[50:65]
	ds_read_b128 v[82:85], v221 offset:25664
	ds_read_b128 v[86:89], v221 offset:34880
	s_waitcnt lgkmcnt(4)
	v_mfma_f32_32x32x16_bf16 v[34:49], v[202:205], v[90:93], v[34:49]
	v_exp_f32_e32 v72, v78
	v_exp_f32_e32 v73, v79
	v_max_f32_e32 v198, v78, v79
	v_add_f32_e32 v79, v72, v73
	v_cvt_pk_bf16_f32 v72, v72, v73
	s_waitcnt lgkmcnt(2)
	v_mfma_f32_32x32x16_bf16 v[50:65], v[74:77], v[66:69], v[50:65]
	ds_read_b128 v[74:77], v221 offset:34912
	v_mfma_f32_32x32x16_bf16 v[18:33], v[194:197], v[90:93], v[18:33]
	v_exp_f32_e32 v78, v80
	v_exp_f32_e32 v94, v81
	v_max_f32_e32 v194, v80, v81
	v_pk_add_f32 v[96:97], v[78:79], v[94:95]
	v_cvt_pk_bf16_f32 v73, v78, v94
	ds_read_b128 v[78:81], v221 offset:25696
	s_waitcnt lgkmcnt(3)
	v_mfma_f32_32x32x16_bf16 v[2:17], v[82:85], v[66:69], v[2:17]
	ds_read_b128 v[82:85], v221 offset:39488
	ds_read_b128 v[90:93], v221 offset:30304
	s_waitcnt lgkmcnt(4)
	v_mfma_f32_32x32x16_bf16 v[34:49], v[86:89], v[66:69], v[34:49]
	ds_read_b128 v[86:89], v221 offset:39520
	v_max3_f32 v0, v0, v198, v194
	ds_bpermute_b32 v244, v191, v0
	v_add_f32_e32 v245, v96, v97
	v_add_f32_e32 v193, v193, v245
	s_xor_b32 s28, s40, 1
	s_mul_i32 s28, s28, 0xac00
	v_add3_u32 v246, s28, v169, v181
	v_add3_u32 v247, s28, v182, v183
	v_add3_u32 v248, s28, v184, v185
	v_add_u32_e32 v249, s28, v168
	s_waitcnt vmcnt(4)
	ds_write_b128 v246, v[146:149]
	s_waitcnt vmcnt(3)
	ds_write_b128 v247, v[150:153]
	s_waitcnt vmcnt(2)
	ds_write_b128 v248, v[154:157]
	v_add_u32_e32 v246, v249, v186
	v_add_u32_e32 v247, v249, v187
	s_waitcnt vmcnt(1)
	ds_write_b128 v246, v[158:161] offset:25600
	s_waitcnt vmcnt(0)
	ds_write_b128 v247, v[162:165] offset:25600
	s_waitcnt lgkmcnt(8)
	v_mfma_f32_32x32x16_bf16 v[18:33], v[82:85], v[66:69], v[18:33]
	v_mfma_f32_32x32x16_bf16 v[2:17], v[78:81], v[70:73], v[2:17]
	s_waitcnt lgkmcnt(7)
	v_mfma_f32_32x32x16_bf16 v[50:65], v[90:93], v[70:73], v[50:65]
	v_mfma_f32_32x32x16_bf16 v[34:49], v[74:77], v[70:73], v[34:49]
	s_waitcnt lgkmcnt(6)
	v_mfma_f32_32x32x16_bf16 v[18:33], v[86:89], v[70:73], v[18:33]
	s_waitcnt lgkmcnt(0)
	v_max_f32_e32 v244, v244, v244
	v_max_f32_e32 v0, v0, v244
	v_cmp_lt_f32_e32 vcc, s87, v0
	s_cbranch_vccz .LBB0_113
	v_max_f32_e32 v0, v0, v0
	v_max_f32_e32 v66, 0, v0
	v_exp_f32_e64 v0, -v66
	v_add_f32_e32 v192, v192, v66
	v_xor_b32_e32 v228, 0x80000000, v192
	v_mov_b32_e32 v229, v228
	v_mov_b32_e32 v230, v228
	v_mov_b32_e32 v231, v228
	v_mov_b32_e32 v232, v228
	v_mov_b32_e32 v233, v228
	v_mov_b32_e32 v234, v228
	v_mov_b32_e32 v235, v228
	v_mov_b32_e32 v236, v228
	v_mov_b32_e32 v237, v228
	v_mov_b32_e32 v238, v228
	v_mov_b32_e32 v239, v228
	v_mov_b32_e32 v240, v228
	v_mov_b32_e32 v241, v228
	v_mov_b32_e32 v242, v228
	v_mov_b32_e32 v243, v228
	v_mul_f32_e32 v193, v193, v0
	v_pk_mul_f32 v[16:17], v[16:17], v[0:1] op_sel_hi:[1,0]
	v_pk_mul_f32 v[14:15], v[14:15], v[0:1] op_sel_hi:[1,0]
	v_pk_mul_f32 v[12:13], v[12:13], v[0:1] op_sel_hi:[1,0]
	v_pk_mul_f32 v[10:11], v[10:11], v[0:1] op_sel_hi:[1,0]
	v_pk_mul_f32 v[8:9], v[8:9], v[0:1] op_sel_hi:[1,0]
	v_pk_mul_f32 v[6:7], v[6:7], v[0:1] op_sel_hi:[1,0]
	v_pk_mul_f32 v[4:5], v[4:5], v[0:1] op_sel_hi:[1,0]
	v_pk_mul_f32 v[2:3], v[2:3], v[0:1] op_sel_hi:[1,0]
	v_pk_mul_f32 v[64:65], v[64:65], v[0:1] op_sel_hi:[1,0]
	v_pk_mul_f32 v[62:63], v[62:63], v[0:1] op_sel_hi:[1,0]
	v_pk_mul_f32 v[60:61], v[60:61], v[0:1] op_sel_hi:[1,0]
	v_pk_mul_f32 v[58:59], v[58:59], v[0:1] op_sel_hi:[1,0]
	v_pk_mul_f32 v[56:57], v[56:57], v[0:1] op_sel_hi:[1,0]
	v_pk_mul_f32 v[54:55], v[54:55], v[0:1] op_sel_hi:[1,0]
	v_pk_mul_f32 v[52:53], v[52:53], v[0:1] op_sel_hi:[1,0]
	v_pk_mul_f32 v[50:51], v[50:51], v[0:1] op_sel_hi:[1,0]
	v_pk_mul_f32 v[48:49], v[48:49], v[0:1] op_sel_hi:[1,0]
	v_pk_mul_f32 v[46:47], v[46:47], v[0:1] op_sel_hi:[1,0]
	v_pk_mul_f32 v[44:45], v[44:45], v[0:1] op_sel_hi:[1,0]
	v_pk_mul_f32 v[42:43], v[42:43], v[0:1] op_sel_hi:[1,0]
	v_pk_mul_f32 v[40:41], v[40:41], v[0:1] op_sel_hi:[1,0]
	v_pk_mul_f32 v[38:39], v[38:39], v[0:1] op_sel_hi:[1,0]
	v_pk_mul_f32 v[36:37], v[36:37], v[0:1] op_sel_hi:[1,0]
	v_pk_mul_f32 v[34:35], v[34:35], v[0:1] op_sel_hi:[1,0]
	v_pk_mul_f32 v[32:33], v[32:33], v[0:1] op_sel_hi:[1,0]
	v_pk_mul_f32 v[30:31], v[30:31], v[0:1] op_sel_hi:[1,0]
	v_pk_mul_f32 v[28:29], v[28:29], v[0:1] op_sel_hi:[1,0]
	v_pk_mul_f32 v[26:27], v[26:27], v[0:1] op_sel_hi:[1,0]
	v_pk_mul_f32 v[24:25], v[24:25], v[0:1] op_sel_hi:[1,0]
	v_pk_mul_f32 v[22:23], v[22:23], v[0:1] op_sel_hi:[1,0]
	v_pk_mul_f32 v[20:21], v[20:21], v[0:1] op_sel_hi:[1,0]
	v_pk_mul_f32 v[18:19], v[18:19], v[0:1] op_sel_hi:[1,0]

.LBB0_481:
	s_cmp_gt_i32 s71, 0x92ff
	s_cbranch_scc1 .LBB0_628
	v_readlane_b32 s0, v254, 40
	v_lshlrev_b32_e32 v0, 3, v222
	s_lshl_b32 s0, s0, 14
	v_lshrrev_b32_e32 v23, 3, v222
	v_and_b32_e32 v4, 56, v0
	s_add_i32 s2, s0, 0
	v_lshrrev_b32_e32 v3, 5, v222
	v_mul_u32_u24_e32 v0, 0x84, v4
	v_lshlrev_b32_e32 v6, 2, v23
	v_readlane_b32 s0, v254, 41
	v_and_b32_e32 v2, 31, v223
	v_add3_u32 v39, s2, v0, v6
	v_or_b32_e32 v0, 2, v3
	v_mov_b32_e32 v6, 0x108
	s_movk_i32 s22, 0x84
	s_mov_b32 s8, s0
	v_lshlrev_b32_e32 v20, 2, v2
	v_mad_u32_u24 v43, v0, s22, v6
	v_mov_b32_e32 v6, 0x318
	v_readlane_b32 s1, v254, 42
	s_ashr_i32 s9, s0, 31
	v_add_u32_e32 v5, s2, v20
	s_lshl_b32 s2, s8, 11
	v_mad_u32_u24 v45, v0, s22, v6
	v_mov_b32_e32 v6, 0x528
	v_readlane_b32 s72, v251, 23
	s_lshl_b64 s[0:1], s[8:9], 21
	s_lshl_b64 s[4:5], s[8:9], 24
	s_ashr_i32 s3, s2, 31
	v_mad_u32_u24 v47, v0, s22, v6
	v_mov_b32_e32 v6, 0x738
	s_lshl_b64 s[6:7], s[8:9], 26
	v_readlane_b32 s74, v251, 25
	s_mul_hi_i32 s10, s8, 0x180000
	s_mul_i32 s11, s8, 0x180000
	v_mad_u32_u24 v49, v0, s22, v6
	v_mov_b32_e32 v6, 0x948
	s_mul_hi_i32 s12, s8, 0x3080000
	s_mul_i32 s13, s8, 0x3080000
	v_readlane_b32 s75, v251, 26
	s_add_u32 s8, s74, s0
	v_mad_u32_u24 v51, v0, s22, v6
	v_mov_b32_e32 v6, 0xb58
	s_addc_u32 s9, s75, s1
	v_mov_b32_e32 v21, v1
	v_mad_u32_u24 v53, v0, s22, v6
	v_readlane_b32 s73, v251, 24
	v_lshl_add_u64 v[6:7], s[8:9], 0, v[20:21]
	s_add_u32 s8, s72, s11
	s_addc_u32 s9, s73, s10
	v_readlane_b32 s76, v251, 27
	v_readlane_b32 s77, v251, 28
	v_readlane_b32 s78, v251, 29
	v_readlane_b32 s79, v251, 30
	v_readlane_b32 s80, v251, 31
	v_readlane_b32 s81, v251, 32
	v_readlane_b32 s82, v251, 33
	v_readlane_b32 s83, v251, 34
	v_readlane_b32 s84, v251, 35
	v_readlane_b32 s85, v251, 36
	v_readlane_b32 s86, v251, 37
	v_readlane_b32 s87, v251, 38
	v_lshl_add_u64 v[8:9], s[8:9], 0, v[20:21]
	v_readlane_b32 s8, v251, 1
	v_readlane_b32 s9, v251, 2
	s_add_u32 s0, s8, s0
	v_readlane_b32 s72, v251, 39
	s_addc_u32 s1, s9, s1
	v_readlane_b32 s86, v251, 53
	v_readlane_b32 s87, v251, 54
	s_add_u32 s8, s86, s4
	v_readlane_b32 s84, v251, 51
	s_addc_u32 s9, s87, s5
	s_lshl_b64 s[2:3], s[2:3], 2
	v_lshl_add_u64 v[10:11], s[0:1], 0, v[20:21]
	v_readlane_b32 s85, v251, 52
	s_add_u32 s0, s84, s2
	v_readlane_b32 s82, v251, 49
	s_addc_u32 s1, s85, s3
	v_readlane_b32 s83, v251, 50
	v_lshl_add_u64 v[12:13], s[8:9], 0, v[20:21]
	s_add_u32 s8, s82, s6
	v_readlane_b32 s80, v251, 47
	s_addc_u32 s9, s83, s7
	v_readlane_b32 s81, v251, 48
	v_lshl_add_u64 v[14:15], s[8:9], 0, v[20:21]
	s_add_u32 s8, s80, s6
	v_readlane_b32 s78, v251, 45
	s_addc_u32 s9, s81, s7
	v_readlane_b32 s79, v251, 46
	s_add_u32 s2, s78, s2
	v_readlane_b32 s76, v251, 43
	s_addc_u32 s3, s79, s3
	v_readlane_b32 s77, v251, 44
	v_lshl_add_u64 v[16:17], s[8:9], 0, v[20:21]
	s_add_u32 s8, s76, s4
	v_readlane_b32 s74, v251, 41
	s_addc_u32 s9, s77, s5
	v_readlane_b32 s75, v251, 42
	v_lshl_add_u64 v[18:19], s[8:9], 0, v[20:21]
	s_add_u32 s8, s74, s4
	v_readlane_b32 s10, v251, 3
	s_addc_u32 s9, s75, s5
	v_readlane_b32 s11, v251, 4
	v_readlane_b32 s73, v251, 40
	s_add_u32 s10, s72, s6
	s_addc_u32 s11, s73, s7
	s_add_u32 s4, s48, s13
	s_addc_u32 s5, s49, s12
	v_or_b32_e32 v25, 8, v23
	v_lshl_add_u64 v[20:21], s[4:5], 0, v[20:21]
	v_lshlrev_b32_e32 v26, 1, v23
	v_or_b32_e32 v27, 16, v23
	v_or_b32_e32 v29, 24, v23
	v_readlane_b32 s4, v252, 16
	v_lshlrev_b32_e32 v22, 8, v23
	v_lshlrev_b32_e32 v24, 8, v25
	v_mul_u32_u24_e32 v41, 0x84, v0
	v_mad_u32_u24 v76, v0, s22, v211
	v_mad_u32_u24 v77, v0, s22, v213
	v_mov_b32_e32 v243, 0x1188
	v_mad_u32_u24 v78, v0, s22, v243
	v_mad_u32_u24 v79, v0, s22, v250
	v_lshlrev_b32_e32 v0, 1, v4
	s_lshl_b32 s12, s71, 5
	v_lshl_or_b32 v81, s71, 6, v26
	v_lshlrev_b32_e32 v26, 8, v27
	v_lshlrev_b32_e32 v28, 8, v29
	v_lshlrev_b32_e32 v30, 13, v23
	v_lshlrev_b32_e32 v32, 13, v25
	v_lshlrev_b32_e32 v34, 13, v27
	v_lshlrev_b32_e32 v36, 13, v29
	v_readlane_b32 s5, v252, 17
	v_bfe_u32 v80, v222, 3, 2
	s_mov_b32 s86, 0xff61b1e6
	s_mov_b32 s87, 0x41000000
	s_movk_i32 s84, 0x2800
	s_mov_b32 s85, 0xc000
	s_mov_b64 s[74:75], 0x100
	s_sub_i32 s13, 0x133f, s12
	s_lshl_b32 s14, s58, 5
	s_lshl_b32 s15, s71, 1
	s_lshl_b32 s16, s58, 1
	s_lshl_b32 s17, s58, 6
	s_lshl_b32 s18, s71, 7
	s_lshl_b32 s19, s58, 7
	v_lshlrev_b32_e32 v22, 1, v22
	v_lshlrev_b32_e32 v24, 1, v24
	v_lshlrev_b32_e32 v26, 1, v26
	v_lshlrev_b32_e32 v28, 1, v28
	v_lshlrev_b32_e32 v30, 1, v30
	v_lshlrev_b32_e32 v32, 1, v32
	v_lshlrev_b32_e32 v34, 1, v34
	v_lshlrev_b32_e32 v36, 1, v36
	v_mad_u32_u24 v82, v3, s22, v5
	v_lshlrev_b32_e32 v38, 9, v23
	v_lshlrev_b32_e32 v40, 11, v23
	v_lshlrev_b32_e32 v42, 9, v25
	v_lshlrev_b32_e32 v44, 11, v25
	v_lshlrev_b32_e32 v46, 9, v27
	v_lshlrev_b32_e32 v48, 11, v27
	v_lshlrev_b32_e32 v50, 9, v29
	v_lshlrev_b32_e32 v52, 11, v29
	v_lshl_add_u64 v[54:55], s[4:5], 0, v[0:1]
	s_branch .LBB0_486
